# P0 x-conversion work re-dealt item-wise (36-37 items per non-fold workgroup, extra items loaded first), on top of tagged-slot LN exchange
# speedup vs baseline: 1.0108x; 1.0059x over previous
.LBB0_38:
	s_add_u32 s24, s64, 0x2400000
	s_mul_i32 s0, s36, 5
	s_addc_u32 s25, s65, 0
	s_add_i32 s3, s0, s12
	s_and_b64 s[0:1], s[4:5], exec
	s_mul_i32 s0, s13, 5
	s_cselect_b32 s3, s66, s3
	s_add_i32 s4, s0, s12
	s_ashr_i32 s5, s4, 31
	s_lshl_b64 s[8:9], s[4:5], 10
	s_lshl_b64 s[14:15], s[4:5], 11
	s_lshl_b64 s[0:1], s[4:5], 9
	s_lshl_b64 s[18:19], s[4:5], 12
	s_mul_i32 s9, s4, 0x600
	s_mul_i32 s15, s4, 0xc00
	v_mov_b32_e32 v14, 0
	s_mov_b32 s34, 0x7fff80
	s_mov_b64 s[20:21], 0x200
	s_mov_b64 s[36:37], 0x3fffff
	s_mov_b32 s40, s3
	s_cmpk_eq_i32 s4, 0x480
	s_cbranch_scc0 .LBB0_40
	s_cmp_eq_u32 s38, 1
	s_cbranch_scc1 .LBB0_55
	s_mov_b32 s38, 5
	s_sub_i32 s7, s66, 32
	v_and_b32_e32 v1, 63, v130
	v_lshrrev_b32_e32 v2, 6, v130
	v_lshl_or_b32 v1, v2, 7, v1
	v_lshlrev_b32_e32 v14, 4, v1
	v_lshlrev_b32_e32 v15, 3, v1
	s_mul_i32 s0, s7, 0x2493
	s_lshr_b32 s0, s0, 16
	s_mul_i32 s1, s0, 7
	s_sub_i32 s1, s7, s1
	s_lshl_b32 s6, s0, 14
	s_mul_i32 s8, s1, 0x1200000
	s_add_i32 s6, s6, s8
	s_lshl_b32 s8, s0, 13
	s_mul_i32 s9, s1, 0x900000
	s_add_i32 s8, s8, s9
	v_add_u32_e32 v4, s6, v14
	global_load_dwordx4 v[132:135], v4, s[16:17] nt
	global_load_dwordx4 v[136:139], v4, s[16:17] offset:1024 nt
	s_cmpk_lt_u32 s7, 0x80
	s_cbranch_scc0 .Lxf_nob
	s_lshl_b32 s6, s7, 14
	s_add_i32 s6, s6, 0x7e00000
	v_add_u32_e32 v5, s6, v14
	global_load_dwordx4 v[140:143], v5, s[16:17] nt
	global_load_dwordx4 v[144:147], v5, s[16:17] offset:1024 nt
.Lxf_nob:
	s_lshl_b32 s0, s3, 14
	s_lshl_b32 s1, s3, 13
	v_add_u32_e32 v2, s0, v14
	v_add_u32_e32 v3, s1, v15
	s_mov_b32 s35, 0
	global_load_dwordx4 v[16:19], v2, s[16:17] nt
	global_load_dwordx4 v[20:23], v2, s[16:17] offset:1024 nt
	v_add_u32_e32 v5, 0x1200000, v2
	global_load_dwordx4 v[24:27], v5, s[16:17] nt
	global_load_dwordx4 v[28:31], v5, s[16:17] offset:1024 nt
	v_add_u32_e32 v6, 0x2400000, v2
	global_load_dwordx4 v[32:35], v6, s[16:17] nt
	global_load_dwordx4 v[36:39], v6, s[16:17] offset:1024 nt
	v_add_u32_e32 v7, 0x3600000, v2
	global_load_dwordx4 v[40:43], v7, s[16:17] nt
	global_load_dwordx4 v[44:47], v7, s[16:17] offset:1024 nt
	v_add_u32_e32 v8, 0x4800000, v2
	global_load_dwordx4 v[48:51], v8, s[16:17] nt
	global_load_dwordx4 v[52:55], v8, s[16:17] offset:1024 nt
	v_add_u32_e32 v9, 0x5a00000, v2
	global_load_dwordx4 v[56:59], v9, s[16:17] nt
	global_load_dwordx4 v[60:63], v9, s[16:17] offset:1024 nt
	v_add_u32_e32 v10, 0x6c00000, v2
	global_load_dwordx4 v[64:67], v10, s[16:17] nt
	global_load_dwordx4 v[68:71], v10, s[16:17] offset:1024 nt
.Lxf_A:
	s_add_i32 s0, s35, 1
	s_cmp_lt_u32 s0, s38
	s_cbranch_scc0 .Lxf_A_last
	v_add_u32_e32 v2, 0x4000, v2
	global_load_dwordx4 v[72:75], v2, s[16:17] nt
	global_load_dwordx4 v[76:79], v2, s[16:17] offset:1024 nt
	v_add_u32_e32 v5, 0x1200000, v2
	global_load_dwordx4 v[80:83], v5, s[16:17] nt
	global_load_dwordx4 v[84:87], v5, s[16:17] offset:1024 nt
	v_add_u32_e32 v6, 0x2400000, v2
	global_load_dwordx4 v[88:91], v6, s[16:17] nt
	global_load_dwordx4 v[92:95], v6, s[16:17] offset:1024 nt
	v_add_u32_e32 v7, 0x3600000, v2
	global_load_dwordx4 v[96:99], v7, s[16:17] nt
	global_load_dwordx4 v[100:103], v7, s[16:17] offset:1024 nt
	v_add_u32_e32 v8, 0x4800000, v2
	global_load_dwordx4 v[104:107], v8, s[16:17] nt
	global_load_dwordx4 v[108:111], v8, s[16:17] offset:1024 nt
	v_add_u32_e32 v9, 0x5a00000, v2
	global_load_dwordx4 v[112:115], v9, s[16:17] nt
	global_load_dwordx4 v[116:119], v9, s[16:17] offset:1024 nt
	v_add_u32_e32 v10, 0x6c00000, v2
	global_load_dwordx4 v[120:123], v10, s[16:17] nt
	global_load_dwordx4 v[124:127], v10, s[16:17] offset:1024 nt
	s_cmp_eq_u32 s35, 0
	s_cbranch_scc1 .Lxf_A_w14
	s_waitcnt vmcnt(28)
	s_branch .Lxf_A_go

.Lxf_A_go:
	v_cvt_pk_bf16_f32 v16, v16, v17
	v_cvt_pk_bf16_f32 v17, v18, v19
	v_cvt_pk_bf16_f32 v20, v20, v21
	v_cvt_pk_bf16_f32 v21, v22, v23
	global_store_dwordx2 v3, v[16:17], s[24:25] sc0 sc1
	global_store_dwordx2 v3, v[20:21], s[24:25] offset:512 sc0 sc1
	v_cvt_pk_bf16_f32 v24, v24, v25
	v_cvt_pk_bf16_f32 v25, v26, v27
	v_cvt_pk_bf16_f32 v28, v28, v29
	v_cvt_pk_bf16_f32 v29, v30, v31
	v_add_u32_e32 v5, 0x900000, v3
	global_store_dwordx2 v5, v[24:25], s[24:25] sc0 sc1
	global_store_dwordx2 v5, v[28:29], s[24:25] offset:512 sc0 sc1
	v_cvt_pk_bf16_f32 v32, v32, v33
	v_cvt_pk_bf16_f32 v33, v34, v35
	v_cvt_pk_bf16_f32 v36, v36, v37
	v_cvt_pk_bf16_f32 v37, v38, v39
	v_add_u32_e32 v6, 0x1200000, v3
	global_store_dwordx2 v6, v[32:33], s[24:25] sc0 sc1
	global_store_dwordx2 v6, v[36:37], s[24:25] offset:512 sc0 sc1
	v_cvt_pk_bf16_f32 v40, v40, v41
	v_cvt_pk_bf16_f32 v41, v42, v43
	v_cvt_pk_bf16_f32 v44, v44, v45
	v_cvt_pk_bf16_f32 v45, v46, v47
	v_add_u32_e32 v7, 0x1b00000, v3
	global_store_dwordx2 v7, v[40:41], s[24:25] sc0 sc1
	global_store_dwordx2 v7, v[44:45], s[24:25] offset:512 sc0 sc1
	v_cvt_pk_bf16_f32 v48, v48, v49
	v_cvt_pk_bf16_f32 v49, v50, v51
	v_cvt_pk_bf16_f32 v52, v52, v53
	v_cvt_pk_bf16_f32 v53, v54, v55
	v_add_u32_e32 v8, 0x2400000, v3
	global_store_dwordx2 v8, v[48:49], s[24:25] sc0 sc1
	global_store_dwordx2 v8, v[52:53], s[24:25] offset:512 sc0 sc1
	v_cvt_pk_bf16_f32 v56, v56, v57
	v_cvt_pk_bf16_f32 v57, v58, v59
	v_cvt_pk_bf16_f32 v60, v60, v61
	v_cvt_pk_bf16_f32 v61, v62, v63
	v_add_u32_e32 v9, 0x2d00000, v3
	global_store_dwordx2 v9, v[56:57], s[24:25] sc0 sc1
	global_store_dwordx2 v9, v[60:61], s[24:25] offset:512 sc0 sc1
	v_cvt_pk_bf16_f32 v64, v64, v65
	v_cvt_pk_bf16_f32 v65, v66, v67
	v_cvt_pk_bf16_f32 v68, v68, v69
	v_cvt_pk_bf16_f32 v69, v70, v71
	v_add_u32_e32 v10, 0x3600000, v3
	global_store_dwordx2 v10, v[64:65], s[24:25] sc0 sc1
	global_store_dwordx2 v10, v[68:69], s[24:25] offset:512 sc0 sc1
	v_add_u32_e32 v3, 0x2000, v3
	s_add_i32 s35, s35, 1
	s_cmp_lt_u32 s35, s38
	s_cbranch_scc1 .Lxf_B
	s_branch .Lxf_tail
.Lxf_B:
	s_add_i32 s0, s35, 1
	s_cmp_lt_u32 s0, s38
	s_cbranch_scc0 .Lxf_B_last
	v_add_u32_e32 v2, 0x4000, v2
	global_load_dwordx4 v[16:19], v2, s[16:17] nt
	global_load_dwordx4 v[20:23], v2, s[16:17] offset:1024 nt
	v_add_u32_e32 v5, 0x1200000, v2
	global_load_dwordx4 v[24:27], v5, s[16:17] nt
	global_load_dwordx4 v[28:31], v5, s[16:17] offset:1024 nt
	v_add_u32_e32 v6, 0x2400000, v2
	global_load_dwordx4 v[32:35], v6, s[16:17] nt
	global_load_dwordx4 v[36:39], v6, s[16:17] offset:1024 nt
	v_add_u32_e32 v7, 0x3600000, v2
	global_load_dwordx4 v[40:43], v7, s[16:17] nt
	global_load_dwordx4 v[44:47], v7, s[16:17] offset:1024 nt
	v_add_u32_e32 v8, 0x4800000, v2
	global_load_dwordx4 v[48:51], v8, s[16:17] nt
	global_load_dwordx4 v[52:55], v8, s[16:17] offset:1024 nt
	v_add_u32_e32 v9, 0x5a00000, v2
	global_load_dwordx4 v[56:59], v9, s[16:17] nt
	global_load_dwordx4 v[60:63], v9, s[16:17] offset:1024 nt
	v_add_u32_e32 v10, 0x6c00000, v2
	global_load_dwordx4 v[64:67], v10, s[16:17] nt
	global_load_dwordx4 v[68:71], v10, s[16:17] offset:1024 nt
	s_waitcnt vmcnt(28)
	s_branch .Lxf_B_go

.Lxf_B_go:
	v_cvt_pk_bf16_f32 v72, v72, v73
	v_cvt_pk_bf16_f32 v73, v74, v75
	v_cvt_pk_bf16_f32 v76, v76, v77
	v_cvt_pk_bf16_f32 v77, v78, v79
	global_store_dwordx2 v3, v[72:73], s[24:25] sc0 sc1
	global_store_dwordx2 v3, v[76:77], s[24:25] offset:512 sc0 sc1
	v_cvt_pk_bf16_f32 v80, v80, v81
	v_cvt_pk_bf16_f32 v81, v82, v83
	v_cvt_pk_bf16_f32 v84, v84, v85
	v_cvt_pk_bf16_f32 v85, v86, v87
	v_add_u32_e32 v5, 0x900000, v3
	global_store_dwordx2 v5, v[80:81], s[24:25] sc0 sc1
	global_store_dwordx2 v5, v[84:85], s[24:25] offset:512 sc0 sc1
	v_cvt_pk_bf16_f32 v88, v88, v89
	v_cvt_pk_bf16_f32 v89, v90, v91
	v_cvt_pk_bf16_f32 v92, v92, v93
	v_cvt_pk_bf16_f32 v93, v94, v95
	v_add_u32_e32 v6, 0x1200000, v3
	global_store_dwordx2 v6, v[88:89], s[24:25] sc0 sc1
	global_store_dwordx2 v6, v[92:93], s[24:25] offset:512 sc0 sc1
	v_cvt_pk_bf16_f32 v96, v96, v97
	v_cvt_pk_bf16_f32 v97, v98, v99
	v_cvt_pk_bf16_f32 v100, v100, v101
	v_cvt_pk_bf16_f32 v101, v102, v103
	v_add_u32_e32 v7, 0x1b00000, v3
	global_store_dwordx2 v7, v[96:97], s[24:25] sc0 sc1
	global_store_dwordx2 v7, v[100:101], s[24:25] offset:512 sc0 sc1
	v_cvt_pk_bf16_f32 v104, v104, v105
	v_cvt_pk_bf16_f32 v105, v106, v107
	v_cvt_pk_bf16_f32 v108, v108, v109
	v_cvt_pk_bf16_f32 v109, v110, v111
	v_add_u32_e32 v8, 0x2400000, v3
	global_store_dwordx2 v8, v[104:105], s[24:25] sc0 sc1
	global_store_dwordx2 v8, v[108:109], s[24:25] offset:512 sc0 sc1
	v_cvt_pk_bf16_f32 v112, v112, v113
	v_cvt_pk_bf16_f32 v113, v114, v115
	v_cvt_pk_bf16_f32 v116, v116, v117
	v_cvt_pk_bf16_f32 v117, v118, v119
	v_add_u32_e32 v9, 0x2d00000, v3
	global_store_dwordx2 v9, v[112:113], s[24:25] sc0 sc1
	global_store_dwordx2 v9, v[116:117], s[24:25] offset:512 sc0 sc1
	v_cvt_pk_bf16_f32 v120, v120, v121
	v_cvt_pk_bf16_f32 v121, v122, v123
	v_cvt_pk_bf16_f32 v124, v124, v125
	v_cvt_pk_bf16_f32 v125, v126, v127
	v_add_u32_e32 v10, 0x3600000, v3
	global_store_dwordx2 v10, v[120:121], s[24:25] sc0 sc1
	global_store_dwordx2 v10, v[124:125], s[24:25] offset:512 sc0 sc1
	v_add_u32_e32 v3, 0x2000, v3
	s_add_i32 s35, s35, 1
	s_cmp_lt_u32 s35, s38
	s_cbranch_scc1 .Lxf_A
.Lxf_tail:
	v_cvt_pk_bf16_f32 v132, v132, v133
	v_cvt_pk_bf16_f32 v133, v134, v135
	v_cvt_pk_bf16_f32 v136, v136, v137
	v_cvt_pk_bf16_f32 v137, v138, v139
	v_add_u32_e32 v4, s8, v15
	global_store_dwordx2 v4, v[132:133], s[24:25] sc0 sc1
	global_store_dwordx2 v4, v[136:137], s[24:25] offset:512 sc0 sc1
	s_cmpk_lt_u32 s7, 0x80
	s_cbranch_scc0 .LBB0_55
	s_lshl_b32 s6, s7, 13
	s_add_i32 s6, s6, 0x3f00000
	v_cvt_pk_bf16_f32 v140, v140, v141
	v_cvt_pk_bf16_f32 v141, v142, v143
	v_cvt_pk_bf16_f32 v144, v144, v145
	v_cvt_pk_bf16_f32 v145, v146, v147
	v_add_u32_e32 v5, s6, v15
	global_store_dwordx2 v5, v[140:141], s[24:25] sc0 sc1
	global_store_dwordx2 v5, v[144:145], s[24:25] offset:512 sc0 sc1
	s_branch .LBB0_55
